# STACK: E28 + E30 (stat conversions) + E35 (RMW loads up front) + E37 (peeled waits relaxed) + E36 (R barrier below S.next)
# speedup vs baseline: 1.0047x; 1.0041x over previous
.LBB0_307:
	s_lshl_b32 s8, s93, 8
	s_add_i32 s8, s8, s46
	s_ashr_i32 s9, s8, 31
	v_lshl_add_u64 v[142:143], s[8:9], 3, v[130:131]
	global_load_dwordx2 v[144:145], v[142:143], off
	global_load_dwordx2 v[154:155], v[142:143], off offset:128
	v_pk_mul_f32 v[156:157], v[114:115], v[126:127]
	v_pk_mul_f32 v[170:171], v[112:113], v[124:125]
	v_pk_mul_f32 v[172:173], v[110:111], v[122:123]
	v_pk_mul_f32 v[174:175], v[108:109], v[120:121]
	v_pk_mul_f32 v[176:177], v[106:107], v[118:119]
	global_load_dwordx2 v[178:179], v[142:143], off offset:256
	global_load_dwordx2 v[126:127], v[142:143], off offset:384
	global_load_dwordx2 v[124:125], v[142:143], off offset:1024
	global_load_dwordx2 v[122:123], v[142:143], off offset:1152
	global_load_dwordx2 v[120:121], v[142:143], off offset:1280
	global_load_dwordx2 v[118:119], v[142:143], off offset:1408
	s_flbit_i32_b32 s8, 0
	s_min_u32 s42, s8, 32
	s_mul_i32 s8, s93, 0x58
	s_sub_i32 s93, 32, s42
	v_pk_mul_f32 v[128:129], v[116:117], v[128:129]
	s_lshl_b32 s9, s92, 1
	s_or_b32 s9, s9, s73
	s_add_i32 s8, s9, s8
	s_ashr_i32 s9, s8, 31
	s_lshl_b64 s[8:9], s[8:9], 15
	s_add_u32 s43, s25, s8
	s_addc_u32 s92, s30, s9
	s_add_u32 s8, s43, s64
	s_addc_u32 s9, s92, s65
	s_add_u32 s8, s8, s88
	s_addc_u32 s9, s9, 0
	v_pk_mul_f32 v[98:99], v[102:103], v[98:99]
	v_pk_mul_f32 v[100:101], v[104:105], v[100:101]
	v_pk_mul_f32 v[90:91], v[94:95], v[90:91]
	v_pk_mul_f32 v[92:93], v[96:97], v[92:93]
	v_pk_mul_f32 v[82:83], v[86:87], v[82:83]
	v_pk_mul_f32 v[84:85], v[88:89], v[84:85]
	v_pk_mul_f32 v[74:75], v[78:79], v[74:75]
	v_pk_mul_f32 v[76:77], v[80:81], v[76:77]
	v_pk_mul_f32 v[66:67], v[70:71], v[66:67]
	v_pk_mul_f32 v[68:69], v[72:73], v[68:69]
	v_pk_mul_f32 v[58:59], v[62:63], v[58:59]
	v_pk_mul_f32 v[60:61], v[64:65], v[60:61]
	v_pk_mul_f32 v[50:51], v[54:55], v[50:51]
	v_pk_mul_f32 v[52:53], v[56:57], v[52:53]
	v_pk_mul_f32 v[42:43], v[46:47], v[42:43]
	v_pk_mul_f32 v[44:45], v[48:49], v[44:45]
	v_pk_mul_f32 v[34:35], v[38:39], v[34:35]
	v_pk_mul_f32 v[36:37], v[40:41], v[36:37]
	v_pk_mul_f32 v[26:27], v[30:31], v[26:27]
	v_pk_mul_f32 v[28:29], v[32:33], v[28:29]
	v_pk_mul_f32 v[18:19], v[22:23], v[18:19]
	v_pk_mul_f32 v[20:21], v[24:25], v[20:21]
	v_pk_mul_f32 v[12:13], v[16:17], v[12:13]
	v_pk_mul_f32 v[10:11], v[14:15], v[10:11]
	v_pk_mul_f32 v[4:5], v[8:9], v[4:5]
	v_pk_mul_f32 v[2:3], v[6:7], v[2:3]
	v_readlane_b32 s97, v252, 18
	v_readlane_b32 s96, v252, 46
	s_waitcnt vmcnt(0)
	v_mov_b32_e32 v146, v145
	v_lshlrev_b64 v[142:143], s42, v[146:147]
	v_min_u32_e32 v142, 1, v142
	s_waitcnt vmcnt(6)
	v_mov_b32_e32 v146, v155
	v_or_b32_e32 v143, v143, v142
	v_cvt_f32_u32_e32 v180, v144
	v_lshlrev_b64 v[144:145], s42, v[146:147]
	v_cvt_f32_u32_e32 v143, v143
	v_min_u32_e32 v146, 1, v144
	v_or_b32_e32 v145, v145, v146
	v_cvt_f32_u32_e32 v154, v154
	v_cvt_f32_u32_e32 v145, v145
	v_fmamk_f32 v142, v180, 0x30000000, v209
	v_ldexp_f32 v143, v143, s93
	v_fmac_f32_e32 v142, 2.0, v143
	v_rsq_f32_e32 v143, v142
	v_fmamk_f32 v144, v154, 0x30000000, v209
	v_ldexp_f32 v145, v145, s93
	v_fmac_f32_e32 v144, 2.0, v145
	v_rsq_f32_e32 v145, v144
	v_mul_f32_e32 v146, 0xbfb8aa3b, v143
	v_pk_mul_f32 v[114:115], v[114:115], v[146:147] op_sel_hi:[1,0]
	v_pk_mul_f32 v[116:117], v[116:117], v[146:147] op_sel_hi:[1,0]
	v_exp_f32_e32 v114, v114
	v_exp_f32_e32 v115, v115
	v_pk_mul_f32 v[110:111], v[110:111], v[146:147] op_sel_hi:[1,0]
	v_pk_mul_f32 v[112:113], v[112:113], v[146:147] op_sel_hi:[1,0]
	v_mul_f32_e32 v146, 0xbfb8aa3b, v145
	v_exp_f32_e32 v116, v116
	v_exp_f32_e32 v117, v117
	v_exp_f32_e32 v110, v110
	v_exp_f32_e32 v111, v111
	v_exp_f32_e32 v112, v112
	v_exp_f32_e32 v113, v113
	v_pk_mul_f32 v[154:155], v[102:103], v[146:147] op_sel_hi:[1,0]
	v_pk_mul_f32 v[106:107], v[106:107], v[146:147] op_sel_hi:[1,0]
	v_exp_f32_e32 v154, v154
	v_exp_f32_e32 v155, v155
	v_pk_mul_f32 v[108:109], v[108:109], v[146:147] op_sel_hi:[1,0]
	v_exp_f32_e32 v106, v106
	v_exp_f32_e32 v107, v107
	v_pk_fma_f32 v[114:115], v[142:143], v[114:115], v[142:143] op_sel_hi:[0,1,0]
	v_pk_mul_f32 v[180:181], v[104:105], v[146:147] op_sel_hi:[1,0]
	v_exp_f32_e32 v108, v108
	v_exp_f32_e32 v109, v109
	v_pk_fma_f32 v[116:117], v[142:143], v[116:117], v[142:143] op_sel_hi:[0,1,0]
	v_rcp_f32_e32 v114, v114
	v_rcp_f32_e32 v115, v115
	v_exp_f32_e32 v180, v180
	v_exp_f32_e32 v181, v181
	v_pk_fma_f32 v[110:111], v[142:143], v[110:111], v[142:143] op_sel_hi:[0,1,0]
	v_pk_fma_f32 v[112:113], v[142:143], v[112:113], v[142:143] op_sel_hi:[0,1,0]
	v_rcp_f32_e32 v116, v116
	v_rcp_f32_e32 v117, v117
	v_rcp_f32_e32 v110, v110
	v_rcp_f32_e32 v111, v111
	v_rcp_f32_e32 v112, v112
	v_rcp_f32_e32 v113, v113
	v_pk_fma_f32 v[142:143], v[144:145], v[154:155], v[144:145] op_sel_hi:[0,1,0]
	v_pk_fma_f32 v[106:107], v[144:145], v[106:107], v[144:145] op_sel_hi:[0,1,0]
	v_rcp_f32_e32 v142, v142
	v_rcp_f32_e32 v143, v143
	v_pk_fma_f32 v[108:109], v[144:145], v[108:109], v[144:145] op_sel_hi:[0,1,0]
	v_rcp_f32_e32 v154, v106
	v_rcp_f32_e32 v155, v107
	v_pk_mul_f32 v[106:107], v[156:157], v[114:115]
	v_pk_fma_f32 v[144:145], v[144:145], v[180:181], v[144:145] op_sel_hi:[0,1,0]
	v_rcp_f32_e32 v180, v108
	v_rcp_f32_e32 v181, v109
	v_pk_mul_f32 v[108:109], v[128:129], v[116:117]
	v_cvt_pk_bf16_f32 v106, v106, v107
	v_pk_mul_f32 v[110:111], v[172:173], v[110:111]
	v_cvt_pk_bf16_f32 v107, v108, v109
	v_pk_mul_f32 v[112:113], v[170:171], v[112:113]
	v_cvt_pk_bf16_f32 v108, v110, v111
	s_waitcnt vmcnt(5)
	v_mov_b32_e32 v146, v179
	v_cvt_pk_bf16_f32 v109, v112, v113
	global_store_dwordx4 v141, v[106:109], s[8:9]
	v_pk_mul_f32 v[102:103], v[98:99], v[142:143]
	v_mov_b32_e32 v99, v146
	v_rcp_f32_e32 v106, v144
	v_rcp_f32_e32 v107, v145
	s_add_u32 s8, s43, s66
	v_pk_mul_f32 v[104:105], v[100:101], v[106:107]
	v_cvt_f32_u32_e32 v100, v178
	v_cvt_f32_u32_e32 v101, v99
	s_addc_u32 s9, s92, s67
	s_add_u32 s8, s8, s88
	v_fmamk_f32 v106, v100, 0x30000000, v209
	v_mov_b32_e32 v100, v101
	v_fmac_f32_e32 v106, 2.0, v100
	v_rsq_f32_e32 v107, v106
	v_pk_mul_f32 v[110:111], v[176:177], v[154:155]
	s_addc_u32 s9, s9, 0
	v_cvt_pk_bf16_f32 v98, v110, v111
	v_pk_mul_f32 v[112:113], v[174:175], v[180:181]
	s_waitcnt vmcnt(5)
	v_mov_b32_e32 v146, v127
	v_cvt_pk_bf16_f32 v99, v112, v113
	v_cvt_pk_bf16_f32 v100, v102, v103
	v_cvt_pk_bf16_f32 v101, v104, v105
	global_store_dwordx4 v141, v[98:101], s[8:9]
	s_add_u32 s8, s43, s70
	s_addc_u32 s9, s92, s71
	v_mul_f32_e32 v98, 0xbfb8aa3b, v107
	v_pk_mul_f32 v[100:101], v[94:95], v[98:99] op_sel_hi:[1,0]
	v_pk_mul_f32 v[94:95], v[86:87], v[98:99] op_sel_hi:[1,0]
	v_pk_mul_f32 v[102:103], v[96:97], v[98:99] op_sel_hi:[1,0]
	v_exp_f32_e32 v94, v94
	v_exp_f32_e32 v95, v95
	v_pk_mul_f32 v[96:97], v[88:89], v[98:99] op_sel_hi:[1,0]
	v_exp_f32_e32 v100, v100
	v_exp_f32_e32 v96, v96
	v_exp_f32_e32 v97, v97
	v_pk_fma_f32 v[94:95], v[106:107], v[94:95], v[106:107] op_sel_hi:[0,1,0]
	v_rcp_f32_e32 v94, v94
	v_rcp_f32_e32 v95, v95
	v_exp_f32_e32 v101, v101
	v_pk_fma_f32 v[96:97], v[106:107], v[96:97], v[106:107] op_sel_hi:[0,1,0]
	v_rcp_f32_e32 v96, v96
	v_rcp_f32_e32 v97, v97
	v_pk_mul_f32 v[86:87], v[82:83], v[94:95]
	v_mov_b32_e32 v83, v146
	v_pk_fma_f32 v[100:101], v[106:107], v[100:101], v[106:107] op_sel_hi:[0,1,0]
	v_rcp_f32_e32 v100, v100
	v_rcp_f32_e32 v101, v101
	v_pk_mul_f32 v[88:89], v[84:85], v[96:97]
	v_cvt_f32_u32_e32 v84, v126
	v_cvt_f32_u32_e32 v85, v83
	v_exp_f32_e32 v102, v102
	v_exp_f32_e32 v103, v103
	v_pk_mul_f32 v[90:91], v[90:91], v[100:101]
	s_add_u32 s8, s8, s88
	v_cvt_pk_bf16_f32 v82, v90, v91
	v_fmamk_f32 v90, v84, 0x30000000, v209
	v_mov_b32_e32 v84, v85
	v_pk_fma_f32 v[102:103], v[106:107], v[102:103], v[106:107] op_sel_hi:[0,1,0]
	v_fmac_f32_e32 v90, 2.0, v84
	v_rcp_f32_e32 v102, v102
	v_rcp_f32_e32 v103, v103
	v_rsq_f32_e32 v91, v90
	s_addc_u32 s9, s9, 0
	s_waitcnt vmcnt(5)
	v_mov_b32_e32 v146, v125
	v_pk_mul_f32 v[92:93], v[92:93], v[102:103]
	s_nop 0
	v_cvt_pk_bf16_f32 v83, v92, v93
	v_cvt_pk_bf16_f32 v84, v86, v87
	v_cvt_pk_bf16_f32 v85, v88, v89
	global_store_dwordx4 v141, v[82:85], s[8:9]
	s_add_u32 s8, s43, s26
	s_addc_u32 s9, s92, s27
	v_mul_f32_e32 v82, 0xbfb8aa3b, v91
	v_pk_mul_f32 v[84:85], v[78:79], v[82:83] op_sel_hi:[1,0]
	v_pk_mul_f32 v[78:79], v[70:71], v[82:83] op_sel_hi:[1,0]
	v_pk_mul_f32 v[86:87], v[80:81], v[82:83] op_sel_hi:[1,0]
	v_exp_f32_e32 v78, v78
	v_exp_f32_e32 v79, v79
	v_pk_mul_f32 v[80:81], v[72:73], v[82:83] op_sel_hi:[1,0]
	v_exp_f32_e32 v84, v84
	v_exp_f32_e32 v80, v80
	v_exp_f32_e32 v81, v81
	v_pk_fma_f32 v[78:79], v[90:91], v[78:79], v[90:91] op_sel_hi:[0,1,0]
	v_rcp_f32_e32 v78, v78
	v_rcp_f32_e32 v79, v79
	v_exp_f32_e32 v85, v85
	v_pk_fma_f32 v[80:81], v[90:91], v[80:81], v[90:91] op_sel_hi:[0,1,0]
	v_rcp_f32_e32 v80, v80
	v_rcp_f32_e32 v81, v81
	v_pk_mul_f32 v[70:71], v[66:67], v[78:79]
	v_mov_b32_e32 v67, v146
	v_pk_fma_f32 v[84:85], v[90:91], v[84:85], v[90:91] op_sel_hi:[0,1,0]
	v_rcp_f32_e32 v84, v84
	v_rcp_f32_e32 v85, v85
	v_pk_mul_f32 v[72:73], v[68:69], v[80:81]
	v_cvt_f32_u32_e32 v68, v124
	v_cvt_f32_u32_e32 v69, v67
	v_exp_f32_e32 v86, v86
	v_exp_f32_e32 v87, v87
	v_pk_mul_f32 v[74:75], v[74:75], v[84:85]
	s_add_u32 s8, s8, s88
	v_cvt_pk_bf16_f32 v66, v74, v75
	v_fmamk_f32 v74, v68, 0x30000000, v209
	v_mov_b32_e32 v68, v69
	v_pk_fma_f32 v[86:87], v[90:91], v[86:87], v[90:91] op_sel_hi:[0,1,0]
	v_fmac_f32_e32 v74, 2.0, v68
	v_rcp_f32_e32 v86, v86
	v_rcp_f32_e32 v87, v87
	v_rsq_f32_e32 v75, v74
	s_addc_u32 s9, s9, 0
	s_waitcnt vmcnt(5)
	v_mov_b32_e32 v146, v123
	v_pk_mul_f32 v[76:77], v[76:77], v[86:87]
	s_nop 0
	v_cvt_pk_bf16_f32 v67, v76, v77
	v_cvt_pk_bf16_f32 v68, v70, v71
	v_cvt_pk_bf16_f32 v69, v72, v73
	global_store_dwordx4 v141, v[66:69], s[8:9]
	s_add_u32 s8, s43, s22
	s_addc_u32 s9, s92, s82
	v_mul_f32_e32 v66, 0xbfb8aa3b, v75
	v_pk_mul_f32 v[68:69], v[62:63], v[66:67] op_sel_hi:[1,0]
	v_pk_mul_f32 v[62:63], v[54:55], v[66:67] op_sel_hi:[1,0]
	v_pk_mul_f32 v[70:71], v[64:65], v[66:67] op_sel_hi:[1,0]
	v_exp_f32_e32 v62, v62
	v_exp_f32_e32 v63, v63
	v_pk_mul_f32 v[64:65], v[56:57], v[66:67] op_sel_hi:[1,0]
	v_exp_f32_e32 v68, v68
	v_exp_f32_e32 v64, v64
	v_exp_f32_e32 v65, v65
	v_pk_fma_f32 v[62:63], v[74:75], v[62:63], v[74:75] op_sel_hi:[0,1,0]
	v_rcp_f32_e32 v62, v62
	v_rcp_f32_e32 v63, v63
	v_exp_f32_e32 v69, v69
	v_pk_fma_f32 v[64:65], v[74:75], v[64:65], v[74:75] op_sel_hi:[0,1,0]
	v_rcp_f32_e32 v64, v64
	v_rcp_f32_e32 v65, v65
	v_pk_mul_f32 v[54:55], v[50:51], v[62:63]
	v_mov_b32_e32 v51, v146
	v_pk_fma_f32 v[68:69], v[74:75], v[68:69], v[74:75] op_sel_hi:[0,1,0]
	v_rcp_f32_e32 v68, v68
	v_rcp_f32_e32 v69, v69
	v_pk_mul_f32 v[56:57], v[52:53], v[64:65]
	v_cvt_f32_u32_e32 v52, v122
	v_cvt_f32_u32_e32 v53, v51
	v_exp_f32_e32 v70, v70
	v_exp_f32_e32 v71, v71
	v_pk_mul_f32 v[58:59], v[58:59], v[68:69]
	s_add_u32 s8, s8, s88
	v_cvt_pk_bf16_f32 v50, v58, v59
	v_fmamk_f32 v58, v52, 0x30000000, v209
	v_mov_b32_e32 v52, v53
	v_pk_fma_f32 v[70:71], v[74:75], v[70:71], v[74:75] op_sel_hi:[0,1,0]
	v_fmac_f32_e32 v58, 2.0, v52
	v_rcp_f32_e32 v70, v70
	v_rcp_f32_e32 v71, v71
	v_rsq_f32_e32 v59, v58
	s_addc_u32 s9, s9, 0
	s_waitcnt vmcnt(5)
	v_mov_b32_e32 v146, v121
	v_pk_mul_f32 v[60:61], v[60:61], v[70:71]
	s_nop 0
	v_cvt_pk_bf16_f32 v51, v60, v61
	v_cvt_pk_bf16_f32 v52, v54, v55
	v_cvt_pk_bf16_f32 v53, v56, v57
	global_store_dwordx4 v141, v[50:53], s[8:9]
	s_add_u32 s8, s43, s12
	s_addc_u32 s9, s92, s83
	v_mul_f32_e32 v50, 0xbfb8aa3b, v59
	v_pk_mul_f32 v[52:53], v[46:47], v[50:51] op_sel_hi:[1,0]
	v_pk_mul_f32 v[46:47], v[38:39], v[50:51] op_sel_hi:[1,0]
	v_pk_mul_f32 v[54:55], v[48:49], v[50:51] op_sel_hi:[1,0]
	v_exp_f32_e32 v46, v46
	v_exp_f32_e32 v47, v47
	v_pk_mul_f32 v[48:49], v[40:41], v[50:51] op_sel_hi:[1,0]
	v_exp_f32_e32 v52, v52
	v_exp_f32_e32 v48, v48
	v_exp_f32_e32 v49, v49
	v_pk_fma_f32 v[46:47], v[58:59], v[46:47], v[58:59] op_sel_hi:[0,1,0]
	v_rcp_f32_e32 v46, v46
	v_rcp_f32_e32 v47, v47
	v_exp_f32_e32 v53, v53
	v_pk_fma_f32 v[48:49], v[58:59], v[48:49], v[58:59] op_sel_hi:[0,1,0]
	v_rcp_f32_e32 v48, v48
	v_rcp_f32_e32 v49, v49
	v_pk_mul_f32 v[38:39], v[34:35], v[46:47]
	v_mov_b32_e32 v35, v146
	v_pk_fma_f32 v[52:53], v[58:59], v[52:53], v[58:59] op_sel_hi:[0,1,0]
	v_rcp_f32_e32 v52, v52
	v_rcp_f32_e32 v53, v53
	v_pk_mul_f32 v[40:41], v[36:37], v[48:49]
	v_cvt_f32_u32_e32 v36, v120
	v_cvt_f32_u32_e32 v37, v35
	v_exp_f32_e32 v54, v54
	v_exp_f32_e32 v55, v55
	v_pk_mul_f32 v[42:43], v[42:43], v[52:53]
	s_add_u32 s8, s8, s88
	v_cvt_pk_bf16_f32 v34, v42, v43
	v_fmamk_f32 v42, v36, 0x30000000, v209
	v_mov_b32_e32 v36, v37
	v_pk_fma_f32 v[54:55], v[58:59], v[54:55], v[58:59] op_sel_hi:[0,1,0]
	v_fmac_f32_e32 v42, 2.0, v36
	v_rcp_f32_e32 v54, v54
	v_rcp_f32_e32 v55, v55
	v_rsq_f32_e32 v43, v42
	s_addc_u32 s9, s9, 0
	s_waitcnt vmcnt(5)
	v_mov_b32_e32 v146, v119
	v_pk_mul_f32 v[44:45], v[44:45], v[54:55]
	s_nop 0
	v_cvt_pk_bf16_f32 v35, v44, v45
	v_cvt_pk_bf16_f32 v36, v38, v39
	v_cvt_pk_bf16_f32 v37, v40, v41
	global_store_dwordx4 v141, v[34:37], s[8:9]
	s_add_u32 s8, s43, s84
	s_addc_u32 s9, s92, s85
	v_mul_f32_e32 v34, 0xbfb8aa3b, v43
	v_pk_mul_f32 v[36:37], v[30:31], v[34:35] op_sel_hi:[1,0]
	v_pk_mul_f32 v[30:31], v[22:23], v[34:35] op_sel_hi:[1,0]
	v_pk_mul_f32 v[38:39], v[32:33], v[34:35] op_sel_hi:[1,0]
	v_exp_f32_e32 v30, v30
	v_exp_f32_e32 v31, v31
	v_pk_mul_f32 v[32:33], v[24:25], v[34:35] op_sel_hi:[1,0]
	v_exp_f32_e32 v36, v36
	v_exp_f32_e32 v32, v32
	v_exp_f32_e32 v33, v33
	v_pk_fma_f32 v[30:31], v[42:43], v[30:31], v[42:43] op_sel_hi:[0,1,0]
	v_rcp_f32_e32 v30, v30
	v_rcp_f32_e32 v31, v31
	v_exp_f32_e32 v37, v37
	v_pk_fma_f32 v[32:33], v[42:43], v[32:33], v[42:43] op_sel_hi:[0,1,0]
	v_rcp_f32_e32 v32, v32
	v_rcp_f32_e32 v33, v33
	v_pk_mul_f32 v[22:23], v[18:19], v[30:31]
	v_mov_b32_e32 v19, v146
	v_pk_fma_f32 v[36:37], v[42:43], v[36:37], v[42:43] op_sel_hi:[0,1,0]
	v_rcp_f32_e32 v36, v36
	v_rcp_f32_e32 v37, v37
	v_pk_mul_f32 v[24:25], v[20:21], v[32:33]
	v_cvt_f32_u32_e32 v20, v118
	v_cvt_f32_u32_e32 v21, v19
	v_exp_f32_e32 v38, v38
	v_exp_f32_e32 v39, v39
	v_pk_mul_f32 v[26:27], v[26:27], v[36:37]
	s_add_u32 s8, s8, s88
	v_cvt_pk_bf16_f32 v18, v26, v27
	v_fmamk_f32 v26, v20, 0x30000000, v209
	v_mov_b32_e32 v20, v21
	v_pk_fma_f32 v[38:39], v[42:43], v[38:39], v[42:43] op_sel_hi:[0,1,0]
	v_fmac_f32_e32 v26, 2.0, v20
	v_rcp_f32_e32 v38, v38
	v_rcp_f32_e32 v39, v39
	v_rsq_f32_e32 v27, v26
	s_addc_u32 s9, s9, 0
	v_pk_mul_f32 v[28:29], v[28:29], v[38:39]
	s_nop 0
	v_cvt_pk_bf16_f32 v19, v28, v29
	v_cvt_pk_bf16_f32 v20, v22, v23
	v_cvt_pk_bf16_f32 v21, v24, v25
	global_store_dwordx4 v141, v[18:21], s[8:9]
	s_add_u32 s8, s43, s86
	s_addc_u32 s9, s92, s87
	v_mul_f32_e32 v18, 0xbfb8aa3b, v27
	v_pk_mul_f32 v[20:21], v[14:15], v[18:19] op_sel_hi:[1,0]
	v_pk_mul_f32 v[22:23], v[16:17], v[18:19] op_sel_hi:[1,0]
	v_pk_mul_f32 v[14:15], v[6:7], v[18:19] op_sel_hi:[1,0]
	v_pk_mul_f32 v[16:17], v[8:9], v[18:19] op_sel_hi:[1,0]
	v_exp_f32_e32 v20, v20
	v_exp_f32_e32 v21, v21
	v_exp_f32_e32 v22, v22
	v_exp_f32_e32 v23, v23
	v_exp_f32_e32 v14, v14
	v_exp_f32_e32 v15, v15
	v_exp_f32_e32 v16, v16
	v_exp_f32_e32 v17, v17
	v_pk_fma_f32 v[20:21], v[26:27], v[20:21], v[26:27] op_sel_hi:[0,1,0]
	v_pk_fma_f32 v[22:23], v[26:27], v[22:23], v[26:27] op_sel_hi:[0,1,0]
	v_pk_fma_f32 v[14:15], v[26:27], v[14:15], v[26:27] op_sel_hi:[0,1,0]
	v_pk_fma_f32 v[16:17], v[26:27], v[16:17], v[26:27] op_sel_hi:[0,1,0]
	v_rcp_f32_e32 v20, v20
	v_rcp_f32_e32 v21, v21
	v_rcp_f32_e32 v22, v22
	v_rcp_f32_e32 v23, v23
	v_rcp_f32_e32 v14, v14
	v_rcp_f32_e32 v15, v15
	v_rcp_f32_e32 v16, v16
	v_rcp_f32_e32 v17, v17
	s_add_u32 s8, s8, s88
	s_addc_u32 s9, s9, 0
	v_pk_mul_f32 v[10:11], v[10:11], v[20:21]
	v_pk_mul_f32 v[12:13], v[12:13], v[22:23]
	v_pk_mul_f32 v[6:7], v[2:3], v[14:15]
	v_pk_mul_f32 v[8:9], v[4:5], v[16:17]
	v_cvt_pk_bf16_f32 v2, v10, v11
	v_cvt_pk_bf16_f32 v3, v12, v13
	v_cvt_pk_bf16_f32 v4, v6, v7
	s_andn2_b64 vcc, exec, s[34:35]
	v_cvt_pk_bf16_f32 v5, v8, v9
	global_store_dwordx4 v141, v[2:5], s[8:9]
	s_mov_b64 s[8:9], -1
	s_cbranch_vccnz .LBB0_293
	s_andn2_b64 vcc, exec, s[44:45]
	s_cbranch_vccnz .LBB0_292
	s_mov_b32 m0, -1
	s_branch .LBB0_292

.Lgk_rs_1:
	v_add_u32_e32 v154, 0x10000, v140
	ds_read_b128 v[132:135], v154
	ds_read_b128 v[142:145], v154 offset:1024
	ds_read_b128 v[170:173], v154 offset:2048
	ds_read_b128 v[174:177], v154 offset:3072
	v_add_u32_e32 v154, 0x14000, v140
	ds_read_b128 v[178:181], v154
	ds_read_b128 v[182:185], v154 offset:1024
	ds_read_b128 v[186:189], v154 offset:2048
	ds_read_b128 v[190:193], v154 offset:3072
	s_add_i32 s23, s21, 0x4000
	s_cmpk_eq_i32 s22, 0x54
	s_cselect_b32 s27, s8, s23
	s_cselect_b32 s26, s9, s13
	s_or_b32 s23, s27, 0x8000
	s_mov_b32 m0, s68
	ds_read_b128 v[194:197], v141
	ds_read_b128 v[198:201], v141 offset:1024
	ds_read_b128 v[202:205], v141 offset:2048
	ds_read_b128 v[228:231], v141 offset:3072
	ds_read_b128 v[232:235], v141 offset:4096
	ds_read_b128 v[236:239], v141 offset:5120
	ds_read_b128 v[240:243], v141 offset:6144
	ds_read_b128 v[244:247], v141 offset:7168
	buffer_load_dwordx4 v136, s[60:63], s21 offen lds
	s_mov_b32 m0, s70
	s_nop 0
	buffer_load_dwordx4 v138, s[60:63], s21 offen lds
	s_waitcnt vmcnt(32)
	s_waitcnt lgkmcnt(0)
	s_setprio 1
	s_barrier
	v_mfma_f32_16x16x32_bf16 v[126:129], v[132:135], v[194:197], 0
	v_mfma_f32_16x16x32_bf16 v[126:129], v[142:145], v[198:201], v[126:129]
	v_mfma_f32_16x16x32_bf16 v[106:109], v[170:173], v[194:197], 0
	v_mfma_f32_16x16x32_bf16 v[106:109], v[174:177], v[198:201], v[106:109]
	v_mfma_f32_16x16x32_bf16 v[110:113], v[186:189], v[194:197], 0
	v_mfma_f32_16x16x32_bf16 v[110:113], v[190:193], v[198:201], v[110:113]
	v_mfma_f32_16x16x32_bf16 v[122:125], v[178:181], v[194:197], 0
	v_mfma_f32_16x16x32_bf16 v[122:125], v[182:185], v[198:201], v[122:125]
	v_mfma_f32_16x16x32_bf16 v[102:105], v[178:181], v[202:205], 0
	v_mfma_f32_16x16x32_bf16 v[102:105], v[182:185], v[228:231], v[102:105]
	v_mfma_f32_16x16x32_bf16 v[98:101], v[186:189], v[202:205], 0
	v_mfma_f32_16x16x32_bf16 v[98:101], v[190:193], v[228:231], v[98:101]
	v_mfma_f32_16x16x32_bf16 v[114:117], v[170:173], v[202:205], 0
	v_mfma_f32_16x16x32_bf16 v[114:117], v[174:177], v[228:231], v[114:117]
	v_mfma_f32_16x16x32_bf16 v[118:121], v[132:135], v[202:205], 0
	v_mfma_f32_16x16x32_bf16 v[118:121], v[142:145], v[228:231], v[118:121]
	v_mfma_f32_16x16x32_bf16 v[94:97], v[132:135], v[232:235], 0
	v_mfma_f32_16x16x32_bf16 v[94:97], v[142:145], v[236:239], v[94:97]
	v_mfma_f32_16x16x32_bf16 v[90:93], v[170:173], v[232:235], 0
	v_mfma_f32_16x16x32_bf16 v[90:93], v[174:177], v[236:239], v[90:93]
	v_mfma_f32_16x16x32_bf16 v[82:85], v[186:189], v[232:235], 0
	v_mfma_f32_16x16x32_bf16 v[82:85], v[190:193], v[236:239], v[82:85]
	v_mfma_f32_16x16x32_bf16 v[86:89], v[178:181], v[232:235], 0
	v_mfma_f32_16x16x32_bf16 v[86:89], v[182:185], v[236:239], v[86:89]
	v_mfma_f32_16x16x32_bf16 v[70:73], v[178:181], v[240:243], 0
	v_mfma_f32_16x16x32_bf16 v[70:73], v[182:185], v[244:247], v[70:73]
	v_mfma_f32_16x16x32_bf16 v[66:69], v[186:189], v[240:243], 0
	v_mfma_f32_16x16x32_bf16 v[66:69], v[190:193], v[244:247], v[66:69]
	v_mfma_f32_16x16x32_bf16 v[74:77], v[170:173], v[240:243], 0
	v_mfma_f32_16x16x32_bf16 v[74:77], v[174:177], v[244:247], v[74:77]
	v_mfma_f32_16x16x32_bf16 v[78:81], v[132:135], v[240:243], 0
	v_mfma_f32_16x16x32_bf16 v[78:81], v[142:145], v[244:247], v[78:81]
	s_barrier
	s_setprio 0
	s_mov_b32 s46, s62
	s_mov_b32 s47, s63
	s_mov_b32 m0, s15
	ds_read_b128 v[194:197], v141 offset:16384
	buffer_load_dwordx4 v137, s[44:47], s26 offen lds
	s_add_i32 s52, s26, 0x160000
	s_mov_b32 m0, s16
	ds_read_b128 v[198:201], v141 offset:17408
	buffer_load_dwordx4 v139, s[44:47], s26 offen lds
	s_mov_b32 m0, s18
	ds_read_b128 v[202:205], v141 offset:18432
	buffer_load_dwordx4 v137, s[44:47], s52 offen lds
	s_mov_b32 m0, s19
	ds_read_b128 v[228:231], v141 offset:19456
	buffer_load_dwordx4 v139, s[44:47], s52 offen lds
	s_mov_b32 m0, s14
	ds_read_b128 v[232:235], v141 offset:20480
	buffer_load_dwordx4 v136, s[60:63], s27 offen lds
	s_mov_b32 m0, s24
	ds_read_b128 v[236:239], v141 offset:21504
	buffer_load_dwordx4 v138, s[60:63], s27 offen lds
	ds_read_b128 v[240:243], v141 offset:22528
	ds_read_b128 v[244:247], v141 offset:23552
	s_cmp_lg_u32 s69, 1
	s_cbranch_scc1 .Lgk_w2_0
	s_waitcnt vmcnt(8)

.Lgk_rs_9:
	v_add_u32_e32 v170, 0x10000, v140
	v_add_u32_e32 v186, 0x14000, v140
	ds_read_b128 v[132:135], v170
	ds_read_b128 v[142:145], v170 offset:1024
	ds_read_b128 v[154:157], v170 offset:2048
	ds_read_b128 v[170:173], v170 offset:3072
	ds_read_b128 v[174:177], v186
	ds_read_b128 v[178:181], v186 offset:1024
	ds_read_b128 v[182:185], v186 offset:2048
	ds_read_b128 v[186:189], v186 offset:3072
	s_add_i32 s23, s13, 0xfff80080
	s_cmp_eq_u32 s22, 28
	s_cselect_b32 s27, s8, s23
	s_cselect_b32 s26, s9, s21
	s_or_b32 s23, s27, 0x80
	s_mov_b32 m0, s70
	ds_read_b128 v[190:193], v141
	ds_read_b128 v[194:197], v141 offset:1024
	ds_read_b128 v[198:201], v141 offset:2048
	ds_read_b128 v[202:205], v141 offset:3072
	ds_read_b128 v[228:231], v141 offset:4096
	ds_read_b128 v[232:235], v141 offset:5120
	ds_read_b128 v[236:239], v141 offset:6144
	ds_read_b128 v[240:243], v141 offset:7168
	buffer_load_dwordx4 v136, s[60:63], s13 offen lds
	s_mov_b32 m0, s72
	s_nop 0
	buffer_load_dwordx4 v138, s[60:63], s13 offen lds
	s_waitcnt vmcnt(32)
	s_waitcnt lgkmcnt(0)
	s_setprio 1
	s_barrier
	v_mfma_f32_16x16x32_bf16 v[126:129], v[132:135], v[190:193], 0
	v_mfma_f32_16x16x32_bf16 v[126:129], v[142:145], v[194:197], v[126:129]
	v_mfma_f32_16x16x32_bf16 v[106:109], v[154:157], v[190:193], 0
	v_mfma_f32_16x16x32_bf16 v[106:109], v[170:173], v[194:197], v[106:109]
	v_mfma_f32_16x16x32_bf16 v[110:113], v[182:185], v[190:193], 0
	v_mfma_f32_16x16x32_bf16 v[110:113], v[186:189], v[194:197], v[110:113]
	v_mfma_f32_16x16x32_bf16 v[122:125], v[174:177], v[190:193], 0
	v_mfma_f32_16x16x32_bf16 v[122:125], v[178:181], v[194:197], v[122:125]
	v_mfma_f32_16x16x32_bf16 v[102:105], v[174:177], v[198:201], 0
	v_mfma_f32_16x16x32_bf16 v[102:105], v[178:181], v[202:205], v[102:105]
	v_mfma_f32_16x16x32_bf16 v[98:101], v[182:185], v[198:201], 0
	v_mfma_f32_16x16x32_bf16 v[98:101], v[186:189], v[202:205], v[98:101]
	v_mfma_f32_16x16x32_bf16 v[114:117], v[154:157], v[198:201], 0
	v_mfma_f32_16x16x32_bf16 v[114:117], v[170:173], v[202:205], v[114:117]
	v_mfma_f32_16x16x32_bf16 v[118:121], v[132:135], v[198:201], 0
	v_mfma_f32_16x16x32_bf16 v[118:121], v[142:145], v[202:205], v[118:121]
	v_mfma_f32_16x16x32_bf16 v[94:97], v[132:135], v[228:231], 0
	v_mfma_f32_16x16x32_bf16 v[94:97], v[142:145], v[232:235], v[94:97]
	v_mfma_f32_16x16x32_bf16 v[90:93], v[154:157], v[228:231], 0
	v_mfma_f32_16x16x32_bf16 v[90:93], v[170:173], v[232:235], v[90:93]
	v_mfma_f32_16x16x32_bf16 v[82:85], v[182:185], v[228:231], 0
	v_mfma_f32_16x16x32_bf16 v[82:85], v[186:189], v[232:235], v[82:85]
	v_mfma_f32_16x16x32_bf16 v[86:89], v[174:177], v[228:231], 0
	v_mfma_f32_16x16x32_bf16 v[86:89], v[178:181], v[232:235], v[86:89]
	v_mfma_f32_16x16x32_bf16 v[70:73], v[174:177], v[236:239], 0
	v_mfma_f32_16x16x32_bf16 v[70:73], v[178:181], v[240:243], v[70:73]
	v_mfma_f32_16x16x32_bf16 v[66:69], v[182:185], v[236:239], 0
	v_mfma_f32_16x16x32_bf16 v[66:69], v[186:189], v[240:243], v[66:69]
	v_mfma_f32_16x16x32_bf16 v[74:77], v[154:157], v[236:239], 0
	v_mfma_f32_16x16x32_bf16 v[74:77], v[170:173], v[240:243], v[74:77]
	v_mfma_f32_16x16x32_bf16 v[78:81], v[132:135], v[236:239], 0
	v_mfma_f32_16x16x32_bf16 v[78:81], v[142:145], v[240:243], v[78:81]
	s_barrier
	s_setprio 0
	s_mov_b32 s46, s62
	s_mov_b32 s47, s63
	s_mov_b32 m0, s15
	ds_read_b128 v[190:193], v141 offset:16384
	buffer_load_dwordx4 v137, s[44:47], s26 offen lds
	s_add_i32 s49, s26, 0x80000
	s_mov_b32 m0, s16
	ds_read_b128 v[194:197], v141 offset:17408
	buffer_load_dwordx4 v139, s[44:47], s26 offen lds
	s_mov_b32 m0, s18
	ds_read_b128 v[198:201], v141 offset:18432
	buffer_load_dwordx4 v137, s[44:47], s49 offen lds
	s_mov_b32 m0, s19
	ds_read_b128 v[202:205], v141 offset:19456
	buffer_load_dwordx4 v139, s[44:47], s49 offen lds
	s_mov_b32 m0, s14
	ds_read_b128 v[228:231], v141 offset:20480
	buffer_load_dwordx4 v136, s[60:63], s27 offen lds
	s_mov_b32 m0, s24
	ds_read_b128 v[232:235], v141 offset:21504
	buffer_load_dwordx4 v138, s[60:63], s27 offen lds
	ds_read_b128 v[236:239], v141 offset:22528
	ds_read_b128 v[240:243], v141 offset:23552
	s_cmp_lg_u32 s71, 1
	s_cbranch_scc1 .Lgk_w2_1
	s_waitcnt vmcnt(8)

.LBB0_1883:
	s_lshl_b32 s8, s93, 8
	s_add_i32 s8, s8, s46
	s_ashr_i32 s9, s8, 31
	v_lshl_add_u64 v[140:141], s[8:9], 3, v[130:131]
	global_load_dwordx2 v[142:143], v[140:141], off
	global_load_dwordx2 v[144:145], v[140:141], off offset:128
	v_pk_mul_f32 v[154:155], v[114:115], v[126:127]
	v_pk_mul_f32 v[156:157], v[112:113], v[124:125]
	v_pk_mul_f32 v[170:171], v[110:111], v[122:123]
	v_pk_mul_f32 v[172:173], v[108:109], v[120:121]
	v_pk_mul_f32 v[174:175], v[106:107], v[118:119]
	global_load_dwordx2 v[176:177], v[140:141], off offset:256
	global_load_dwordx2 v[126:127], v[140:141], off offset:384
	global_load_dwordx2 v[124:125], v[140:141], off offset:1024
	global_load_dwordx2 v[122:123], v[140:141], off offset:1152
	global_load_dwordx2 v[120:121], v[140:141], off offset:1280
	global_load_dwordx2 v[118:119], v[140:141], off offset:1408
	s_flbit_i32_b32 s8, 0
	s_min_u32 s42, s8, 32
	s_mul_i32 s8, s93, 0x58
	s_sub_i32 s93, 32, s42
	v_pk_mul_f32 v[128:129], v[116:117], v[128:129]
	s_lshl_b32 s9, s90, 1
	s_or_b32 s9, s9, s73
	s_add_i32 s8, s9, s8
	s_ashr_i32 s9, s8, 31
	s_lshl_b64 s[8:9], s[8:9], 15
	s_add_u32 s43, s25, s8
	s_addc_u32 s90, s30, s9
	s_add_u32 s8, s43, s66
	s_addc_u32 s9, s90, s67
	s_add_u32 s8, s8, s88
	s_addc_u32 s9, s9, 0
	v_pk_mul_f32 v[98:99], v[102:103], v[98:99]
	v_pk_mul_f32 v[100:101], v[104:105], v[100:101]
	v_pk_mul_f32 v[90:91], v[94:95], v[90:91]
	v_pk_mul_f32 v[92:93], v[96:97], v[92:93]
	v_pk_mul_f32 v[82:83], v[86:87], v[82:83]
	v_pk_mul_f32 v[84:85], v[88:89], v[84:85]
	v_pk_mul_f32 v[74:75], v[78:79], v[74:75]
	v_pk_mul_f32 v[76:77], v[80:81], v[76:77]
	v_pk_mul_f32 v[66:67], v[70:71], v[66:67]
	v_pk_mul_f32 v[68:69], v[72:73], v[68:69]
	v_pk_mul_f32 v[58:59], v[62:63], v[58:59]
	v_pk_mul_f32 v[60:61], v[64:65], v[60:61]
	v_pk_mul_f32 v[50:51], v[54:55], v[50:51]
	v_pk_mul_f32 v[52:53], v[56:57], v[52:53]
	v_pk_mul_f32 v[42:43], v[46:47], v[42:43]
	v_pk_mul_f32 v[44:45], v[48:49], v[44:45]
	v_pk_mul_f32 v[34:35], v[38:39], v[34:35]
	v_pk_mul_f32 v[36:37], v[40:41], v[36:37]
	v_pk_mul_f32 v[26:27], v[30:31], v[26:27]
	v_pk_mul_f32 v[28:29], v[32:33], v[28:29]
	v_pk_mul_f32 v[18:19], v[22:23], v[18:19]
	v_pk_mul_f32 v[20:21], v[24:25], v[20:21]
	v_pk_mul_f32 v[12:13], v[16:17], v[12:13]
	v_pk_mul_f32 v[10:11], v[14:15], v[10:11]
	v_pk_mul_f32 v[4:5], v[8:9], v[4:5]
	v_pk_mul_f32 v[2:3], v[6:7], v[2:3]
	v_readlane_b32 s96, v252, 46
	s_waitcnt vmcnt(0)
	v_cvt_f32_u32_e32 v139, v142
	v_mov_b32_e32 v146, v143
	v_mov_b32_e32 v141, v146
	v_mov_b32_e32 v146, v145
	v_lshlrev_b64 v[142:143], s42, v[146:147]
	v_fmamk_f32 v140, v139, 0x30000000, v209
	v_cvt_f32_u32_e32 v139, v141
	v_min_u32_e32 v145, 1, v142
	v_or_b32_e32 v141, v143, v145
	v_cvt_f32_u32_e32 v144, v144
	v_cvt_f32_u32_e32 v141, v141
	v_fmac_f32_e32 v140, 2.0, v139
	v_rsq_f32_e32 v139, v140
	v_fmamk_f32 v142, v144, 0x30000000, v209
	v_ldexp_f32 v141, v141, s93
	v_fmac_f32_e32 v142, 2.0, v141
	v_rsq_f32_e32 v141, v142
	v_mul_f32_e32 v144, 0xbfb8aa3b, v139
	v_pk_mul_f32 v[114:115], v[114:115], v[144:145] op_sel_hi:[1,0]
	v_pk_mul_f32 v[116:117], v[116:117], v[144:145] op_sel_hi:[1,0]
	v_exp_f32_e32 v114, v114
	v_exp_f32_e32 v115, v115
	v_pk_mul_f32 v[110:111], v[110:111], v[144:145] op_sel_hi:[1,0]
	v_pk_mul_f32 v[112:113], v[112:113], v[144:145] op_sel_hi:[1,0]
	v_mul_f32_e32 v144, 0xbfb8aa3b, v141
	v_exp_f32_e32 v116, v116
	v_exp_f32_e32 v117, v117
	v_exp_f32_e32 v110, v110
	v_exp_f32_e32 v111, v111
	v_exp_f32_e32 v112, v112
	v_exp_f32_e32 v113, v113
	v_pk_mul_f32 v[178:179], v[102:103], v[144:145] op_sel_hi:[1,0]
	v_pk_mul_f32 v[106:107], v[106:107], v[144:145] op_sel_hi:[1,0]
	v_exp_f32_e32 v178, v178
	v_exp_f32_e32 v179, v179
	v_pk_mul_f32 v[108:109], v[108:109], v[144:145] op_sel_hi:[1,0]
	v_pk_mul_f32 v[144:145], v[104:105], v[144:145] op_sel_hi:[1,0]
	v_exp_f32_e32 v106, v106
	v_exp_f32_e32 v107, v107
	v_pk_fma_f32 v[114:115], v[140:141], v[114:115], v[140:141] op_sel_hi:[0,1,0]
	v_exp_f32_e32 v108, v108
	v_exp_f32_e32 v109, v109
	v_exp_f32_e32 v144, v144
	v_exp_f32_e32 v145, v145
	v_pk_fma_f32 v[116:117], v[140:141], v[116:117], v[140:141] op_sel_hi:[0,1,0]
	v_rcp_f32_e32 v114, v114
	v_rcp_f32_e32 v115, v115
	v_pk_fma_f32 v[110:111], v[140:141], v[110:111], v[140:141] op_sel_hi:[0,1,0]
	v_pk_fma_f32 v[112:113], v[140:141], v[112:113], v[140:141] op_sel_hi:[0,1,0]
	v_rcp_f32_e32 v116, v116
	v_rcp_f32_e32 v117, v117
	v_rcp_f32_e32 v110, v110
	v_rcp_f32_e32 v111, v111
	v_rcp_f32_e32 v112, v112
	v_rcp_f32_e32 v113, v113
	v_pk_fma_f32 v[140:141], v[142:143], v[178:179], v[142:143] op_sel_hi:[0,1,0]
	v_pk_fma_f32 v[106:107], v[142:143], v[106:107], v[142:143] op_sel_hi:[0,1,0]
	v_rcp_f32_e32 v140, v140
	v_rcp_f32_e32 v141, v141
	v_pk_fma_f32 v[108:109], v[142:143], v[108:109], v[142:143] op_sel_hi:[0,1,0]
	v_pk_fma_f32 v[142:143], v[142:143], v[144:145], v[142:143] op_sel_hi:[0,1,0]
	v_rcp_f32_e32 v144, v106
	v_rcp_f32_e32 v145, v107
	v_pk_mul_f32 v[106:107], v[154:155], v[114:115]
	v_rcp_f32_e32 v178, v108
	v_rcp_f32_e32 v179, v109
	v_pk_mul_f32 v[108:109], v[128:129], v[116:117]
	v_cvt_pk_bf16_f32 v106, v106, v107
	v_pk_mul_f32 v[110:111], v[170:171], v[110:111]
	v_cvt_pk_bf16_f32 v107, v108, v109
	v_pk_mul_f32 v[112:113], v[156:157], v[112:113]
	v_cvt_pk_bf16_f32 v108, v110, v111
	v_mov_b32_e32 v146, v177
	v_cvt_pk_bf16_f32 v109, v112, v113
	global_store_dwordx4 v138, v[106:109], s[8:9]
	v_pk_mul_f32 v[102:103], v[98:99], v[140:141]
	v_mov_b32_e32 v99, v146
	v_rcp_f32_e32 v106, v142
	v_rcp_f32_e32 v107, v143
	s_add_u32 s8, s43, s68
	v_pk_mul_f32 v[104:105], v[100:101], v[106:107]
	v_cvt_f32_u32_e32 v100, v176
	v_cvt_f32_u32_e32 v101, v99
	s_addc_u32 s9, s90, s69
	s_add_u32 s8, s8, s88
	v_fmamk_f32 v106, v100, 0x30000000, v209
	v_mov_b32_e32 v100, v101
	v_fmac_f32_e32 v106, 2.0, v100
	v_rsq_f32_e32 v107, v106
	v_pk_mul_f32 v[110:111], v[174:175], v[144:145]
	s_addc_u32 s9, s9, 0
	v_cvt_pk_bf16_f32 v98, v110, v111
	v_pk_mul_f32 v[112:113], v[172:173], v[178:179]
	v_mov_b32_e32 v146, v127
	v_cvt_pk_bf16_f32 v99, v112, v113
	v_cvt_pk_bf16_f32 v100, v102, v103
	v_cvt_pk_bf16_f32 v101, v104, v105
	global_store_dwordx4 v138, v[98:101], s[8:9]
	s_add_u32 s8, s43, s70
	s_addc_u32 s9, s90, s71
	v_mul_f32_e32 v98, 0xbfb8aa3b, v107
	v_pk_mul_f32 v[100:101], v[94:95], v[98:99] op_sel_hi:[1,0]
	v_pk_mul_f32 v[94:95], v[86:87], v[98:99] op_sel_hi:[1,0]
	v_pk_mul_f32 v[102:103], v[96:97], v[98:99] op_sel_hi:[1,0]
	v_exp_f32_e32 v94, v94
	v_exp_f32_e32 v95, v95
	v_pk_mul_f32 v[96:97], v[88:89], v[98:99] op_sel_hi:[1,0]
	v_exp_f32_e32 v100, v100
	v_exp_f32_e32 v96, v96
	v_exp_f32_e32 v97, v97
	v_pk_fma_f32 v[94:95], v[106:107], v[94:95], v[106:107] op_sel_hi:[0,1,0]
	v_rcp_f32_e32 v94, v94
	v_rcp_f32_e32 v95, v95
	v_exp_f32_e32 v101, v101
	v_pk_fma_f32 v[96:97], v[106:107], v[96:97], v[106:107] op_sel_hi:[0,1,0]
	v_rcp_f32_e32 v96, v96
	v_rcp_f32_e32 v97, v97
	v_pk_mul_f32 v[86:87], v[82:83], v[94:95]
	v_mov_b32_e32 v83, v146
	v_pk_fma_f32 v[100:101], v[106:107], v[100:101], v[106:107] op_sel_hi:[0,1,0]
	v_rcp_f32_e32 v100, v100
	v_rcp_f32_e32 v101, v101
	v_pk_mul_f32 v[88:89], v[84:85], v[96:97]
	v_cvt_f32_u32_e32 v84, v126
	v_cvt_f32_u32_e32 v85, v83
	v_exp_f32_e32 v102, v102
	v_exp_f32_e32 v103, v103
	v_pk_mul_f32 v[90:91], v[90:91], v[100:101]
	s_add_u32 s8, s8, s88
	v_cvt_pk_bf16_f32 v82, v90, v91
	v_fmamk_f32 v90, v84, 0x30000000, v209
	v_mov_b32_e32 v84, v85
	v_pk_fma_f32 v[102:103], v[106:107], v[102:103], v[106:107] op_sel_hi:[0,1,0]
	v_fmac_f32_e32 v90, 2.0, v84
	v_rcp_f32_e32 v102, v102
	v_rcp_f32_e32 v103, v103
	v_rsq_f32_e32 v91, v90
	s_addc_u32 s9, s9, 0
	v_mov_b32_e32 v146, v125
	v_pk_mul_f32 v[92:93], v[92:93], v[102:103]
	s_nop 0
	v_cvt_pk_bf16_f32 v83, v92, v93
	v_cvt_pk_bf16_f32 v84, v86, v87
	v_cvt_pk_bf16_f32 v85, v88, v89
	global_store_dwordx4 v138, v[82:85], s[8:9]
	s_add_u32 s8, s43, s26
	s_addc_u32 s9, s90, s27
	v_mul_f32_e32 v82, 0xbfb8aa3b, v91
	v_pk_mul_f32 v[84:85], v[78:79], v[82:83] op_sel_hi:[1,0]
	v_pk_mul_f32 v[78:79], v[70:71], v[82:83] op_sel_hi:[1,0]
	v_pk_mul_f32 v[86:87], v[80:81], v[82:83] op_sel_hi:[1,0]
	v_exp_f32_e32 v78, v78
	v_exp_f32_e32 v79, v79
	v_pk_mul_f32 v[80:81], v[72:73], v[82:83] op_sel_hi:[1,0]
	v_exp_f32_e32 v84, v84
	v_exp_f32_e32 v80, v80
	v_exp_f32_e32 v81, v81
	v_pk_fma_f32 v[78:79], v[90:91], v[78:79], v[90:91] op_sel_hi:[0,1,0]
	v_rcp_f32_e32 v78, v78
	v_rcp_f32_e32 v79, v79
	v_exp_f32_e32 v85, v85
	v_pk_fma_f32 v[80:81], v[90:91], v[80:81], v[90:91] op_sel_hi:[0,1,0]
	v_rcp_f32_e32 v80, v80
	v_rcp_f32_e32 v81, v81
	v_pk_mul_f32 v[70:71], v[66:67], v[78:79]
	v_mov_b32_e32 v67, v146
	v_pk_fma_f32 v[84:85], v[90:91], v[84:85], v[90:91] op_sel_hi:[0,1,0]
	v_rcp_f32_e32 v84, v84
	v_rcp_f32_e32 v85, v85
	v_pk_mul_f32 v[72:73], v[68:69], v[80:81]
	v_cvt_f32_u32_e32 v68, v124
	v_cvt_f32_u32_e32 v69, v67
	v_exp_f32_e32 v86, v86
	v_exp_f32_e32 v87, v87
	v_pk_mul_f32 v[74:75], v[74:75], v[84:85]
	s_add_u32 s8, s8, s88
	v_cvt_pk_bf16_f32 v66, v74, v75
	v_fmamk_f32 v74, v68, 0x30000000, v209
	v_mov_b32_e32 v68, v69
	v_pk_fma_f32 v[86:87], v[90:91], v[86:87], v[90:91] op_sel_hi:[0,1,0]
	v_fmac_f32_e32 v74, 2.0, v68
	v_rcp_f32_e32 v86, v86
	v_rcp_f32_e32 v87, v87
	v_rsq_f32_e32 v75, v74
	s_addc_u32 s9, s9, 0
	v_mov_b32_e32 v146, v123
	v_pk_mul_f32 v[76:77], v[76:77], v[86:87]
	s_nop 0
	v_cvt_pk_bf16_f32 v67, v76, v77
	v_cvt_pk_bf16_f32 v68, v70, v71
	v_cvt_pk_bf16_f32 v69, v72, v73
	global_store_dwordx4 v138, v[66:69], s[8:9]
	s_add_u32 s8, s43, s82
	s_addc_u32 s9, s90, s84
	v_mul_f32_e32 v66, 0xbfb8aa3b, v75
	v_pk_mul_f32 v[68:69], v[62:63], v[66:67] op_sel_hi:[1,0]
	v_pk_mul_f32 v[62:63], v[54:55], v[66:67] op_sel_hi:[1,0]
	v_pk_mul_f32 v[70:71], v[64:65], v[66:67] op_sel_hi:[1,0]
	v_exp_f32_e32 v62, v62
	v_exp_f32_e32 v63, v63
	v_pk_mul_f32 v[64:65], v[56:57], v[66:67] op_sel_hi:[1,0]
	v_exp_f32_e32 v68, v68
	v_exp_f32_e32 v64, v64
	v_exp_f32_e32 v65, v65
	v_pk_fma_f32 v[62:63], v[74:75], v[62:63], v[74:75] op_sel_hi:[0,1,0]
	v_rcp_f32_e32 v62, v62
	v_rcp_f32_e32 v63, v63
	v_exp_f32_e32 v69, v69
	v_pk_fma_f32 v[64:65], v[74:75], v[64:65], v[74:75] op_sel_hi:[0,1,0]
	v_rcp_f32_e32 v64, v64
	v_rcp_f32_e32 v65, v65
	v_pk_mul_f32 v[54:55], v[50:51], v[62:63]
	v_mov_b32_e32 v51, v146
	v_pk_fma_f32 v[68:69], v[74:75], v[68:69], v[74:75] op_sel_hi:[0,1,0]
	v_rcp_f32_e32 v68, v68
	v_rcp_f32_e32 v69, v69
	v_pk_mul_f32 v[56:57], v[52:53], v[64:65]
	v_cvt_f32_u32_e32 v52, v122
	v_cvt_f32_u32_e32 v53, v51
	v_exp_f32_e32 v70, v70
	v_exp_f32_e32 v71, v71
	v_pk_mul_f32 v[58:59], v[58:59], v[68:69]
	s_add_u32 s8, s8, s88
	v_cvt_pk_bf16_f32 v50, v58, v59
	v_fmamk_f32 v58, v52, 0x30000000, v209
	v_mov_b32_e32 v52, v53
	v_pk_fma_f32 v[70:71], v[74:75], v[70:71], v[74:75] op_sel_hi:[0,1,0]
	v_fmac_f32_e32 v58, 2.0, v52
	v_rcp_f32_e32 v70, v70
	v_rcp_f32_e32 v71, v71
	v_rsq_f32_e32 v59, v58
	s_addc_u32 s9, s9, 0
	v_mov_b32_e32 v146, v121
	v_pk_mul_f32 v[60:61], v[60:61], v[70:71]
	s_nop 0
	v_cvt_pk_bf16_f32 v51, v60, v61
	v_cvt_pk_bf16_f32 v52, v54, v55
	v_cvt_pk_bf16_f32 v53, v56, v57
	global_store_dwordx4 v138, v[50:53], s[8:9]
	s_add_u32 s8, s43, s85
	s_addc_u32 s9, s90, s22
	v_mul_f32_e32 v50, 0xbfb8aa3b, v59
	v_pk_mul_f32 v[52:53], v[46:47], v[50:51] op_sel_hi:[1,0]
	v_pk_mul_f32 v[46:47], v[38:39], v[50:51] op_sel_hi:[1,0]
	v_pk_mul_f32 v[54:55], v[48:49], v[50:51] op_sel_hi:[1,0]
	v_exp_f32_e32 v46, v46
	v_exp_f32_e32 v47, v47
	v_pk_mul_f32 v[48:49], v[40:41], v[50:51] op_sel_hi:[1,0]
	v_exp_f32_e32 v52, v52
	v_exp_f32_e32 v48, v48
	v_exp_f32_e32 v49, v49
	v_pk_fma_f32 v[46:47], v[58:59], v[46:47], v[58:59] op_sel_hi:[0,1,0]
	v_rcp_f32_e32 v46, v46
	v_rcp_f32_e32 v47, v47
	v_exp_f32_e32 v53, v53
	v_pk_fma_f32 v[48:49], v[58:59], v[48:49], v[58:59] op_sel_hi:[0,1,0]
	v_rcp_f32_e32 v48, v48
	v_rcp_f32_e32 v49, v49
	v_pk_mul_f32 v[38:39], v[34:35], v[46:47]
	v_mov_b32_e32 v35, v146
	v_pk_fma_f32 v[52:53], v[58:59], v[52:53], v[58:59] op_sel_hi:[0,1,0]
	v_rcp_f32_e32 v52, v52
	v_rcp_f32_e32 v53, v53
	v_pk_mul_f32 v[40:41], v[36:37], v[48:49]
	v_cvt_f32_u32_e32 v36, v120
	v_cvt_f32_u32_e32 v37, v35
	v_exp_f32_e32 v54, v54
	v_exp_f32_e32 v55, v55
	v_pk_mul_f32 v[42:43], v[42:43], v[52:53]
	s_add_u32 s8, s8, s88
	v_cvt_pk_bf16_f32 v34, v42, v43
	v_fmamk_f32 v42, v36, 0x30000000, v209
	v_mov_b32_e32 v36, v37
	v_pk_fma_f32 v[54:55], v[58:59], v[54:55], v[58:59] op_sel_hi:[0,1,0]
	v_fmac_f32_e32 v42, 2.0, v36
	v_rcp_f32_e32 v54, v54
	v_rcp_f32_e32 v55, v55
	v_rsq_f32_e32 v43, v42
	s_addc_u32 s9, s9, 0
	v_mov_b32_e32 v146, v119
	v_pk_mul_f32 v[44:45], v[44:45], v[54:55]
	s_nop 0
	v_cvt_pk_bf16_f32 v35, v44, v45
	v_cvt_pk_bf16_f32 v36, v38, v39
	v_cvt_pk_bf16_f32 v37, v40, v41
	global_store_dwordx4 v138, v[34:37], s[8:9]
	s_add_u32 s8, s43, s83
	s_addc_u32 s9, s90, s12
	v_mul_f32_e32 v34, 0xbfb8aa3b, v43
	v_pk_mul_f32 v[36:37], v[30:31], v[34:35] op_sel_hi:[1,0]
	v_pk_mul_f32 v[30:31], v[22:23], v[34:35] op_sel_hi:[1,0]
	v_pk_mul_f32 v[38:39], v[32:33], v[34:35] op_sel_hi:[1,0]
	v_exp_f32_e32 v30, v30
	v_exp_f32_e32 v31, v31
	v_pk_mul_f32 v[32:33], v[24:25], v[34:35] op_sel_hi:[1,0]
	v_exp_f32_e32 v36, v36
	v_exp_f32_e32 v32, v32
	v_exp_f32_e32 v33, v33
	v_pk_fma_f32 v[30:31], v[42:43], v[30:31], v[42:43] op_sel_hi:[0,1,0]
	v_rcp_f32_e32 v30, v30
	v_rcp_f32_e32 v31, v31
	v_exp_f32_e32 v37, v37
	v_pk_fma_f32 v[32:33], v[42:43], v[32:33], v[42:43] op_sel_hi:[0,1,0]
	v_rcp_f32_e32 v32, v32
	v_rcp_f32_e32 v33, v33
	v_pk_mul_f32 v[22:23], v[18:19], v[30:31]
	v_mov_b32_e32 v19, v146
	v_pk_fma_f32 v[36:37], v[42:43], v[36:37], v[42:43] op_sel_hi:[0,1,0]
	v_rcp_f32_e32 v36, v36
	v_rcp_f32_e32 v37, v37
	v_pk_mul_f32 v[24:25], v[20:21], v[32:33]
	v_cvt_f32_u32_e32 v20, v118
	v_cvt_f32_u32_e32 v21, v19
	v_exp_f32_e32 v38, v38
	v_exp_f32_e32 v39, v39
	v_pk_mul_f32 v[26:27], v[26:27], v[36:37]
	s_add_u32 s8, s8, s88
	v_cvt_pk_bf16_f32 v18, v26, v27
	v_fmamk_f32 v26, v20, 0x30000000, v209
	v_mov_b32_e32 v20, v21
	v_pk_fma_f32 v[38:39], v[42:43], v[38:39], v[42:43] op_sel_hi:[0,1,0]
	v_fmac_f32_e32 v26, 2.0, v20
	v_rcp_f32_e32 v38, v38
	v_rcp_f32_e32 v39, v39
	v_rsq_f32_e32 v27, v26
	s_addc_u32 s9, s9, 0
	v_pk_mul_f32 v[28:29], v[28:29], v[38:39]
	s_nop 0
	v_cvt_pk_bf16_f32 v19, v28, v29
	v_cvt_pk_bf16_f32 v20, v22, v23
	v_cvt_pk_bf16_f32 v21, v24, v25
	global_store_dwordx4 v138, v[18:21], s[8:9]
	s_add_u32 s8, s43, s86
	s_addc_u32 s9, s90, s87
	v_mul_f32_e32 v18, 0xbfb8aa3b, v27
	v_pk_mul_f32 v[20:21], v[14:15], v[18:19] op_sel_hi:[1,0]
	v_pk_mul_f32 v[22:23], v[16:17], v[18:19] op_sel_hi:[1,0]
	v_pk_mul_f32 v[14:15], v[6:7], v[18:19] op_sel_hi:[1,0]
	v_pk_mul_f32 v[16:17], v[8:9], v[18:19] op_sel_hi:[1,0]
	v_exp_f32_e32 v20, v20
	v_exp_f32_e32 v21, v21
	v_exp_f32_e32 v22, v22
	v_exp_f32_e32 v23, v23
	v_exp_f32_e32 v14, v14
	v_exp_f32_e32 v15, v15
	v_exp_f32_e32 v16, v16
	v_exp_f32_e32 v17, v17
	v_pk_fma_f32 v[20:21], v[26:27], v[20:21], v[26:27] op_sel_hi:[0,1,0]
	v_pk_fma_f32 v[22:23], v[26:27], v[22:23], v[26:27] op_sel_hi:[0,1,0]
	v_pk_fma_f32 v[14:15], v[26:27], v[14:15], v[26:27] op_sel_hi:[0,1,0]
	v_pk_fma_f32 v[16:17], v[26:27], v[16:17], v[26:27] op_sel_hi:[0,1,0]
	v_rcp_f32_e32 v20, v20
	v_rcp_f32_e32 v21, v21
	v_rcp_f32_e32 v22, v22
	v_rcp_f32_e32 v23, v23
	v_rcp_f32_e32 v14, v14
	v_rcp_f32_e32 v15, v15
	v_rcp_f32_e32 v16, v16
	v_rcp_f32_e32 v17, v17
	s_add_u32 s8, s8, s88
	s_addc_u32 s9, s9, 0
	v_pk_mul_f32 v[10:11], v[10:11], v[20:21]
	v_pk_mul_f32 v[12:13], v[12:13], v[22:23]
	v_pk_mul_f32 v[6:7], v[2:3], v[14:15]
	v_pk_mul_f32 v[8:9], v[4:5], v[16:17]
	v_cvt_pk_bf16_f32 v2, v10, v11
	v_cvt_pk_bf16_f32 v3, v12, v13
	v_cvt_pk_bf16_f32 v4, v6, v7
	s_andn2_b64 vcc, exec, s[48:49]
	v_cvt_pk_bf16_f32 v5, v8, v9
	global_store_dwordx4 v138, v[2:5], s[8:9]
	s_mov_b64 s[8:9], -1
	s_cbranch_vccnz .LBB0_1869
	s_andn2_b64 vcc, exec, s[44:45]
	s_cbranch_vccnz .LBB0_1868
	s_mov_b32 m0, -1
	s_branch .LBB0_1868

.Lgk_rs_11:
	v_add_u32_e32 v170, 0x10000, v140
	v_add_u32_e32 v186, 0x14000, v140
	ds_read_b128 v[132:135], v170
	ds_read_b128 v[142:145], v170 offset:1024
	ds_read_b128 v[154:157], v170 offset:2048
	ds_read_b128 v[170:173], v170 offset:3072
	ds_read_b128 v[174:177], v186
	ds_read_b128 v[178:181], v186 offset:1024
	ds_read_b128 v[182:185], v186 offset:2048
	ds_read_b128 v[186:189], v186 offset:3072
	s_add_i32 s26, s21, 0x4000
	s_cmpk_eq_i32 s22, 0x54
	s_cselect_b32 s52, s8, s26
	s_cselect_b32 s27, s9, s13
	s_or_b32 s26, s52, 0x8000
	s_mov_b32 m0, s84
	ds_read_b128 v[190:193], v141
	ds_read_b128 v[194:197], v141 offset:1024
	ds_read_b128 v[198:201], v141 offset:2048
	ds_read_b128 v[202:205], v141 offset:3072
	ds_read_b128 v[228:231], v141 offset:4096
	ds_read_b128 v[232:235], v141 offset:5120
	ds_read_b128 v[236:239], v141 offset:6144
	ds_read_b128 v[240:243], v141 offset:7168
	buffer_load_dwordx4 v136, s[60:63], s21 offen lds
	s_mov_b32 m0, s16
	s_nop 0
	buffer_load_dwordx4 v138, s[60:63], s21 offen lds
	s_waitcnt vmcnt(32)
	s_waitcnt lgkmcnt(0)
	s_setprio 1
	s_barrier
	v_mfma_f32_16x16x32_bf16 v[126:129], v[132:135], v[190:193], 0
	v_mfma_f32_16x16x32_bf16 v[126:129], v[142:145], v[194:197], v[126:129]
	v_mfma_f32_16x16x32_bf16 v[106:109], v[154:157], v[190:193], 0
	v_mfma_f32_16x16x32_bf16 v[106:109], v[170:173], v[194:197], v[106:109]
	v_mfma_f32_16x16x32_bf16 v[110:113], v[182:185], v[190:193], 0
	v_mfma_f32_16x16x32_bf16 v[110:113], v[186:189], v[194:197], v[110:113]
	v_mfma_f32_16x16x32_bf16 v[122:125], v[174:177], v[190:193], 0
	v_mfma_f32_16x16x32_bf16 v[122:125], v[178:181], v[194:197], v[122:125]
	v_mfma_f32_16x16x32_bf16 v[102:105], v[174:177], v[198:201], 0
	v_mfma_f32_16x16x32_bf16 v[102:105], v[178:181], v[202:205], v[102:105]
	v_mfma_f32_16x16x32_bf16 v[98:101], v[182:185], v[198:201], 0
	v_mfma_f32_16x16x32_bf16 v[98:101], v[186:189], v[202:205], v[98:101]
	v_mfma_f32_16x16x32_bf16 v[114:117], v[154:157], v[198:201], 0
	v_mfma_f32_16x16x32_bf16 v[114:117], v[170:173], v[202:205], v[114:117]
	v_mfma_f32_16x16x32_bf16 v[118:121], v[132:135], v[198:201], 0
	v_mfma_f32_16x16x32_bf16 v[118:121], v[142:145], v[202:205], v[118:121]
	v_mfma_f32_16x16x32_bf16 v[94:97], v[132:135], v[228:231], 0
	v_mfma_f32_16x16x32_bf16 v[94:97], v[142:145], v[232:235], v[94:97]
	v_mfma_f32_16x16x32_bf16 v[90:93], v[154:157], v[228:231], 0
	v_mfma_f32_16x16x32_bf16 v[90:93], v[170:173], v[232:235], v[90:93]
	v_mfma_f32_16x16x32_bf16 v[82:85], v[182:185], v[228:231], 0
	v_mfma_f32_16x16x32_bf16 v[82:85], v[186:189], v[232:235], v[82:85]
	v_mfma_f32_16x16x32_bf16 v[86:89], v[174:177], v[228:231], 0
	v_mfma_f32_16x16x32_bf16 v[86:89], v[178:181], v[232:235], v[86:89]
	v_mfma_f32_16x16x32_bf16 v[70:73], v[174:177], v[236:239], 0
	v_mfma_f32_16x16x32_bf16 v[70:73], v[178:181], v[240:243], v[70:73]
	v_mfma_f32_16x16x32_bf16 v[66:69], v[182:185], v[236:239], 0
	v_mfma_f32_16x16x32_bf16 v[66:69], v[186:189], v[240:243], v[66:69]
	v_mfma_f32_16x16x32_bf16 v[74:77], v[154:157], v[236:239], 0
	v_mfma_f32_16x16x32_bf16 v[74:77], v[170:173], v[240:243], v[74:77]
	v_mfma_f32_16x16x32_bf16 v[78:81], v[132:135], v[236:239], 0
	v_mfma_f32_16x16x32_bf16 v[78:81], v[142:145], v[240:243], v[78:81]
	s_barrier
	s_setprio 0
	s_mov_b32 s46, s62
	s_mov_b32 s47, s63
	s_mov_b32 m0, s18
	ds_read_b128 v[190:193], v141 offset:16384
	buffer_load_dwordx4 v137, s[44:47], s27 offen lds
	s_add_i32 s53, s27, 0x160000
	s_mov_b32 m0, s19
	ds_read_b128 v[194:197], v141 offset:17408
	buffer_load_dwordx4 v139, s[44:47], s27 offen lds
	s_mov_b32 m0, s24
	ds_read_b128 v[198:201], v141 offset:18432
	buffer_load_dwordx4 v137, s[44:47], s53 offen lds
	s_mov_b32 m0, s25
	ds_read_b128 v[202:205], v141 offset:19456
	buffer_load_dwordx4 v139, s[44:47], s53 offen lds
	s_mov_b32 m0, s14
	ds_read_b128 v[228:231], v141 offset:20480
	buffer_load_dwordx4 v136, s[60:63], s52 offen lds
	s_mov_b32 m0, s30
	ds_read_b128 v[232:235], v141 offset:21504
	buffer_load_dwordx4 v138, s[60:63], s52 offen lds
	ds_read_b128 v[236:239], v141 offset:22528
	ds_read_b128 v[240:243], v141 offset:23552
	s_cmp_lg_u32 s85, 1
	s_cbranch_scc1 .Lgk_w2_2
	s_waitcnt vmcnt(8)

.Lgk_rs_13:
	v_add_u32_e32 v142, 0x10000, v188
	v_add_u32_e32 v182, 0x14000, v188
	ds_read_b128 v[130:133], v142
	ds_read_b128 v[134:137], v142 offset:1024
	ds_read_b128 v[138:141], v142 offset:2048
	ds_read_b128 v[142:145], v142 offset:3072
	ds_read_b128 v[154:157], v182
	ds_read_b128 v[174:177], v182 offset:1024
	ds_read_b128 v[178:181], v182 offset:2048
	ds_read_b128 v[190:193], v182 offset:3072
	s_add_i32 s24, s13, 0xfff80080
	s_cmp_eq_u32 s22, 28
	s_cselect_b32 s52, s8, s24
	s_cselect_b32 s25, s9, s21
	s_or_b32 s24, s52, 0x80
	s_mov_b32 m0, s68
	ds_read_b128 v[194:197], v189
	ds_read_b128 v[198:201], v189 offset:1024
	ds_read_b128 v[202:205], v189 offset:2048
	ds_read_b128 v[228:231], v189 offset:3072
	ds_read_b128 v[232:235], v189 offset:4096
	ds_read_b128 v[236:239], v189 offset:5120
	ds_read_b128 v[240:243], v189 offset:6144
	ds_read_b128 v[244:247], v189 offset:7168
	buffer_load_dwordx4 v184, s[60:63], s13 offen lds
	s_mov_b32 m0, s70
	s_nop 0
	buffer_load_dwordx4 v186, s[60:63], s13 offen lds
	s_waitcnt vmcnt(32)
	s_waitcnt lgkmcnt(0)
	s_setprio 1
	s_barrier
	v_mfma_f32_16x16x32_bf16 v[126:129], v[130:133], v[194:197], 0
	v_mfma_f32_16x16x32_bf16 v[126:129], v[134:137], v[198:201], v[126:129]
	v_mfma_f32_16x16x32_bf16 v[122:125], v[138:141], v[194:197], 0
	v_mfma_f32_16x16x32_bf16 v[122:125], v[142:145], v[198:201], v[122:125]
	v_mfma_f32_16x16x32_bf16 v[114:117], v[178:181], v[194:197], 0
	v_mfma_f32_16x16x32_bf16 v[114:117], v[190:193], v[198:201], v[114:117]
	v_mfma_f32_16x16x32_bf16 v[118:121], v[154:157], v[194:197], 0
	v_mfma_f32_16x16x32_bf16 v[118:121], v[174:177], v[198:201], v[118:121]
	v_mfma_f32_16x16x32_bf16 v[102:105], v[154:157], v[202:205], 0
	v_mfma_f32_16x16x32_bf16 v[102:105], v[174:177], v[228:231], v[102:105]
	v_mfma_f32_16x16x32_bf16 v[98:101], v[178:181], v[202:205], 0
	v_mfma_f32_16x16x32_bf16 v[98:101], v[190:193], v[228:231], v[98:101]
	v_mfma_f32_16x16x32_bf16 v[106:109], v[138:141], v[202:205], 0
	v_mfma_f32_16x16x32_bf16 v[106:109], v[142:145], v[228:231], v[106:109]
	v_mfma_f32_16x16x32_bf16 v[110:113], v[130:133], v[202:205], 0
	v_mfma_f32_16x16x32_bf16 v[110:113], v[134:137], v[228:231], v[110:113]
	v_mfma_f32_16x16x32_bf16 v[94:97], v[130:133], v[232:235], 0
	v_mfma_f32_16x16x32_bf16 v[94:97], v[134:137], v[236:239], v[94:97]
	v_mfma_f32_16x16x32_bf16 v[90:93], v[138:141], v[232:235], 0
	v_mfma_f32_16x16x32_bf16 v[90:93], v[142:145], v[236:239], v[90:93]
	v_mfma_f32_16x16x32_bf16 v[82:85], v[178:181], v[232:235], 0
	v_mfma_f32_16x16x32_bf16 v[82:85], v[190:193], v[236:239], v[82:85]
	v_mfma_f32_16x16x32_bf16 v[86:89], v[154:157], v[232:235], 0
	v_mfma_f32_16x16x32_bf16 v[86:89], v[174:177], v[236:239], v[86:89]
	v_mfma_f32_16x16x32_bf16 v[70:73], v[154:157], v[240:243], 0
	v_mfma_f32_16x16x32_bf16 v[70:73], v[174:177], v[244:247], v[70:73]
	v_mfma_f32_16x16x32_bf16 v[66:69], v[178:181], v[240:243], 0
	v_mfma_f32_16x16x32_bf16 v[66:69], v[190:193], v[244:247], v[66:69]
	v_mfma_f32_16x16x32_bf16 v[74:77], v[138:141], v[240:243], 0
	v_mfma_f32_16x16x32_bf16 v[74:77], v[142:145], v[244:247], v[74:77]
	v_mfma_f32_16x16x32_bf16 v[78:81], v[130:133], v[240:243], 0
	v_mfma_f32_16x16x32_bf16 v[78:81], v[134:137], v[244:247], v[78:81]
	s_barrier
	s_setprio 0
	s_mov_b32 s46, s62
	s_mov_b32 s47, s63
	s_mov_b32 m0, s16
	ds_read_b128 v[194:197], v189 offset:16384
	buffer_load_dwordx4 v185, s[44:47], s25 offen lds
	s_add_i32 s53, s25, 0x80000
	s_mov_b32 m0, s18
	ds_read_b128 v[198:201], v189 offset:17408
	buffer_load_dwordx4 v187, s[44:47], s25 offen lds
	s_mov_b32 m0, s19
	ds_read_b128 v[202:205], v189 offset:18432
	buffer_load_dwordx4 v185, s[44:47], s53 offen lds
	s_mov_b32 m0, s23
	ds_read_b128 v[228:231], v189 offset:19456
	buffer_load_dwordx4 v187, s[44:47], s53 offen lds
	s_mov_b32 m0, s15
	ds_read_b128 v[232:235], v189 offset:20480
	buffer_load_dwordx4 v184, s[60:63], s52 offen lds
	s_mov_b32 m0, s26
	ds_read_b128 v[236:239], v189 offset:21504
	buffer_load_dwordx4 v186, s[60:63], s52 offen lds
	ds_read_b128 v[240:243], v189 offset:22528
	ds_read_b128 v[244:247], v189 offset:23552
	s_cmp_lg_u32 s69, 1
	s_cbranch_scc1 .Lgk_w2_3
	s_waitcnt vmcnt(8)
